# MLA K/V prefetch ladders replaced by straight-line address select (v_cndmask) plus straight-line LDS staging writes
# baseline (speedup 1.0000x reference)
; #define LAS __attribute__((address_space(3)))
; template <int NT, int DQK, int DV, int MODE, int PD, class Src> ...
;     ...
; #pragma unroll
;   for (int u = 0; u < PD; ++u) if (kc0 + u < kc1) ABL_LOAD(u, kc0 + u);
;   for (int kcb = kc0; kcb < kc1; kcb += PD) {
; #pragma unroll
;     for (int u = 0; u < PD; ++u) {
;       const int kc = kcb + u;
;       if (kc < kc1) {
;         LAS unsigned char* buf = lds + ((kc - kc0) & 1) * BUF;
; #pragma unroll
;         for (int rr = 0; rr < NKR; ++rr) { const int idx = tid + 512 * rr; if (idx < NKI) { const int row = idx / KCH, ch = idx % KCH; *(LAS u32x4*)(buf + row * KSTR + ch * 16) = kreg[u][rr]; } }
; #pragma unroll
;         for (int rr = 0; rr < NVR; ++rr) { const int idx = tid + 512 * rr; if (idx < NVI) { const int row = idx / VCH, ch = idx % VCH; *(LAS u32x4*)(buf + KB + row * VSTR + ch * 16) = vreg[u][rr]; } }
;         if (kc + PD < kc1) ABL_LOAD(u, kc + PD);
.LBB0_762:
	s_or_b64 exec, exec, s[20:21]
	s_add_i32 s70, s72, 3
	s_cmp_ge_u32 s70, s65
	s_cselect_b64 s[52:53], -1, 0
	s_cmp_lt_u32 s70, s65
	s_cbranch_scc0 .LBB0_768
	s_lshl_b32 s8, s70, 6
	s_mul_hi_u32 s101, s8, s82
	s_mul_i32 s100, s8, s82
	v_lshl_add_u64 v[26:27], v[208:209], 0, s[100:101]
	v_lshl_add_u64 v[28:29], v[212:213], 0, s[40:41]
	v_lshl_add_u64 v[28:29], v[28:29], 0, s[78:79]
	v_cndmask_b32_e64 v26, v28, v26, s[16:17]
	v_cndmask_b32_e64 v27, v29, v27, s[16:17]
	global_load_dwordx4 v[26:29], v[26:27], off
	v_lshl_add_u64 v[34:35], v[216:217], 0, s[40:41]
	v_add_co_u32_e32 v34, vcc, 0x16060000, v34
	s_nop 1
	v_addc_co_u32_e32 v35, vcc, 0, v35, vcc
	global_load_dwordx4 v[34:37], v[34:35], off offset:128
	s_and_saveexec_b64 s[20:21], s[12:13]
	s_cbranch_execz .Lpfk_0
	v_lshl_add_u64 v[30:31], v[210:211], 0, s[100:101]
	v_lshl_add_u64 v[32:33], v[214:215], 0, s[40:41]
	v_lshl_add_u64 v[32:33], v[32:33], 0, s[78:79]
	v_cndmask_b32_e64 v30, v32, v30, s[18:19]
	v_cndmask_b32_e64 v31, v33, v31, s[18:19]
	global_load_dwordx4 v[30:33], v[30:31], off

; __device__ __forceinline__ float ex2(float x) { return __builtin_amdgcn_exp2f(x); }
;   __device__ __forceinline__ bf16_t* W() const { return (bf16_t*)(ws + WS_W); }
; template <int NT, int NKK, int NDT, int MODE, bool MASK> ...
;     ...
;   for (int j = 0; j < NT; ++j) {
;     float mx = -INFINITY;
; #pragma unroll
;     for (int t = 0; t < 4; ++t)
; #pragma unroll
;       for (int i = 0; i < 4; ++i) {
;         if (MASK) { const int kp = kpos0 + 16 * t + 4 * lg + i; if (!mask_ok<MODE>(tq[j], kp, W)) s[j][t][i] = -INFINITY; }
;         mx = fmaxf(mx, s[j][t][i]);
;       }
;     mx = max_x16_x32(mx);
;     if (__any(mx > m[j] + 8.0f / c)) {
;       const float mnew = fmaxf(m[j], mx);
;       const float ms2 = (mnew == -INFINITY) ? 0.f : mnew;
;       const float alpha = ex2((m[j] - ms2) * c);
;       m[j] = mnew; l[j] *= alpha;
; #pragma unroll
;       for (int dt = 0; dt < NDT; ++dt) o[j][dt] *= alpha;
;     }
.LBB0_772:
	v_mul_f32_e32 v186, 0x3e16c740, v187
	v_cmp_neq_f32_e32 vcc, s81, v187
	s_nop 1
	v_cndmask_b32_e32 v186, 0, v186, vcc
	v_fma_f32 v182, v182, s88, -v186
	v_exp_f32_e32 v205, v182
	v_fma_f32 v182, v183, s88, -v186
	v_exp_f32_e32 v207, v182
	v_fma_f32 v182, v184, s88, -v186
	v_exp_f32_e32 v246, v182
	v_fma_f32 v182, v185, s88, -v186
	v_exp_f32_e32 v247, v182
	v_fma_f32 v178, v178, s88, -v186
	v_exp_f32_e32 v248, v178
	v_fma_f32 v178, v179, s88, -v186
	v_add_f32_e32 v182, v207, v205
	v_exp_f32_e32 v249, v178
	v_fma_f32 v178, v180, s88, -v186
	v_add_f32_e32 v182, v246, v182
	v_exp_f32_e32 v250, v178
	v_fma_f32 v178, v181, s88, -v186
	v_add_f32_e32 v182, v247, v182
	v_exp_f32_e32 v251, v178
	v_fma_f32 v174, v174, s88, -v186
	v_add_f32_e32 v178, v248, v182
	v_exp_f32_e32 v252, v174
	v_fma_f32 v174, v175, s88, -v186
	v_add_f32_e32 v178, v249, v178
	v_exp_f32_e32 v231, v174
	v_fma_f32 v174, v176, s88, -v186
	v_add_f32_e32 v178, v250, v178
	v_exp_f32_e32 v229, v174
	v_fma_f32 v174, v177, s88, -v186
	v_add_f32_e32 v178, v251, v178
	v_exp_f32_e32 v230, v174
	v_fma_f32 v170, v170, s88, -v186
	v_add_f32_e32 v174, v252, v178
	v_exp_f32_e32 v232, v170
	v_fma_f32 v170, v171, s88, -v186
	v_add_f32_e32 v174, v231, v174
	v_exp_f32_e32 v228, v170
	v_fma_f32 v170, v172, s88, -v186
	v_add_f32_e32 v174, v229, v174
	v_exp_f32_e32 v196, v170
	v_fma_f32 v170, v173, s88, -v186
	v_add_f32_e32 v174, v230, v174
	v_exp_f32_e32 v173, v170
	v_add_f32_e32 v170, v232, v174
	v_add_f32_e32 v170, v228, v170
	v_add_f32_e32 v170, v196, v170
	v_add_f32_e32 v170, v173, v170
	v_add_f32_e32 v224, v224, v170
	v_max3_f32 v170, v189, v150, v151
	v_max3_f32 v170, v170, v152, v153
	v_max3_f32 v170, v170, v142, v143
	v_max3_f32 v170, v170, v144, v145
	v_mov_b32_e32 v171, v170
	s_nop 1
	v_permlane16_swap_b32_e32 v170, v171
	v_max_f32_e32 v170, v170, v171
	v_mov_b32_e32 v171, v170
	s_nop 1
	v_permlane32_swap_b32_e32 v170, v171
	v_max_f32_e32 v170, v170, v171
	v_add_f32_e32 v171, 0x4259535f, v223
	v_cmp_gt_f32_e32 vcc, v170, v171
	s_cbranch_vccz .LBB0_786
	v_max_f32_e32 v170, v170, v170
	v_max_f32_e32 v171, v223, v223
	v_max_f32_e32 v197, v171, v170
	v_cmp_neq_f32_e32 vcc, s81, v197
	s_nop 1
	v_cndmask_b32_e32 v170, 0, v197, vcc
	v_sub_f32_e32 v170, v223, v170
	v_mul_f32_e32 v170, 0x3e16c740, v170
	v_exp_f32_e32 v170, v170
	v_mov_b32_e32 v223, v197
	v_mul_f32_e32 v225, v225, v170
	v_pk_mul_f32 v[84:85], v[84:85], v[170:171] op_sel_hi:[1,0]
	v_pk_mul_f32 v[82:83], v[82:83], v[170:171] op_sel_hi:[1,0]
	v_pk_mul_f32 v[80:81], v[80:81], v[170:171] op_sel_hi:[1,0]
	v_pk_mul_f32 v[78:79], v[78:79], v[170:171] op_sel_hi:[1,0]
	v_pk_mul_f32 v[72:73], v[72:73], v[170:171] op_sel_hi:[1,0]
	v_pk_mul_f32 v[70:71], v[70:71], v[170:171] op_sel_hi:[1,0]
	v_pk_mul_f32 v[64:65], v[64:65], v[170:171] op_sel_hi:[1,0]
	v_pk_mul_f32 v[62:63], v[62:63], v[170:171] op_sel_hi:[1,0]
	s_branch .LBB0_787
.LBB0_786:
	v_mov_b32_e32 v197, v223

; #define LAS __attribute__((address_space(3)))
; template <int NT, int DQK, int DV, int MODE, int PD, class Src> ...
;     ...
; #pragma unroll
;   for (int u = 0; u < PD; ++u) if (kc0 + u < kc1) ABL_LOAD(u, kc0 + u);
;   for (int kcb = kc0; kcb < kc1; kcb += PD) {
; #pragma unroll
;     for (int u = 0; u < PD; ++u) {
;       const int kc = kcb + u;
;       if (kc < kc1) {
;         LAS unsigned char* buf = lds + ((kc - kc0) & 1) * BUF;
; #pragma unroll
;         for (int rr = 0; rr < NKR; ++rr) { const int idx = tid + 512 * rr; if (idx < NKI) { const int row = idx / KCH, ch = idx % KCH; *(LAS u32x4*)(buf + row * KSTR + ch * 16) = kreg[u][rr]; } }
; #pragma unroll
;         for (int rr = 0; rr < NVR; ++rr) { const int idx = tid + 512 * rr; if (idx < NVI) { const int row = idx / VCH, ch = idx % VCH; *(LAS u32x4*)(buf + KB + row * VSTR + ch * 16) = vreg[u][rr]; } }
;         if (kc + PD < kc1) ABL_LOAD(u, kc + PD);
.LBB0_805:
	s_lshl_b32 s8, s72, 6
	s_addk_i32 s8, 0x100
	s_mul_hi_u32 s101, s8, s82
	s_mul_i32 s100, s8, s82
	v_lshl_add_u64 v[38:39], v[208:209], 0, s[100:101]
	v_lshl_add_u64 v[40:41], v[212:213], 0, s[40:41]
	s_mov_b64 s[74:75], 0x16080000
	v_lshl_add_u64 v[40:41], v[40:41], 0, s[74:75]
	v_cndmask_b32_e64 v38, v40, v38, s[16:17]
	v_cndmask_b32_e64 v39, v41, v39, s[16:17]
	global_load_dwordx4 v[38:41], v[38:39], off
	v_lshl_add_u64 v[42:43], v[216:217], 0, s[40:41]
	v_add_co_u32_e32 v42, vcc, 0x16080000, v42
	s_nop 1
	v_addc_co_u32_e32 v43, vcc, 0, v43, vcc
	global_load_dwordx4 v[42:45], v[42:43], off offset:128
	s_and_saveexec_b64 s[20:21], s[12:13]
	s_cbranch_execz .Lpfk_1
	v_lshl_add_u64 v[46:47], v[210:211], 0, s[100:101]
	v_lshl_add_u64 v[48:49], v[214:215], 0, s[40:41]
	s_mov_b64 s[8:9], 0x16080000
	v_lshl_add_u64 v[48:49], v[48:49], 0, s[8:9]
	v_cndmask_b32_e64 v46, v48, v46, s[18:19]
	v_cndmask_b32_e64 v47, v49, v47, s[18:19]
	global_load_dwordx4 v[46:49], v[46:47], off

; __device__ __forceinline__ float ex2(float x) { return __builtin_amdgcn_exp2f(x); }
;   __device__ __forceinline__ bf16_t* W() const { return (bf16_t*)(ws + WS_W); }
; template <int NT, int NKK, int NDT, int MODE, bool MASK> ...
;     ...
;   for (int j = 0; j < NT; ++j) {
;     float mx = -INFINITY;
; #pragma unroll
;     for (int t = 0; t < 4; ++t)
; #pragma unroll
;       for (int i = 0; i < 4; ++i) {
;         if (MASK) { const int kp = kpos0 + 16 * t + 4 * lg + i; if (!mask_ok<MODE>(tq[j], kp, W)) s[j][t][i] = -INFINITY; }
;         mx = fmaxf(mx, s[j][t][i]);
;       }
;     mx = max_x16_x32(mx);
;     if (__any(mx > m[j] + 8.0f / c)) {
;       const float mnew = fmaxf(m[j], mx);
;       const float ms2 = (mnew == -INFINITY) ? 0.f : mnew;
;       const float alpha = ex2((m[j] - ms2) * c);
;       m[j] = mnew; l[j] *= alpha;
; #pragma unroll
;       for (int dt = 0; dt < NDT; ++dt) o[j][dt] *= alpha;
;     }
.LBB0_814:
	v_mul_f32_e32 v186, 0x3e16c740, v187
	v_cmp_neq_f32_e32 vcc, s81, v187
	s_nop 1
	v_cndmask_b32_e32 v186, 0, v186, vcc
	v_fma_f32 v182, v182, s88, -v186
	v_exp_f32_e32 v205, v182
	v_fma_f32 v182, v183, s88, -v186
	v_exp_f32_e32 v207, v182
	v_fma_f32 v182, v184, s88, -v186
	v_exp_f32_e32 v246, v182
	v_fma_f32 v182, v185, s88, -v186
	v_exp_f32_e32 v247, v182
	v_fma_f32 v178, v178, s88, -v186
	v_exp_f32_e32 v248, v178
	v_fma_f32 v178, v179, s88, -v186
	v_add_f32_e32 v182, v207, v205
	v_exp_f32_e32 v249, v178
	v_fma_f32 v178, v180, s88, -v186
	v_add_f32_e32 v182, v246, v182
	v_exp_f32_e32 v250, v178
	v_fma_f32 v178, v181, s88, -v186
	v_add_f32_e32 v182, v247, v182
	v_exp_f32_e32 v251, v178
	v_fma_f32 v174, v174, s88, -v186
	v_add_f32_e32 v178, v248, v182
	v_exp_f32_e32 v252, v174
	v_fma_f32 v174, v175, s88, -v186
	v_add_f32_e32 v178, v249, v178
	v_exp_f32_e32 v231, v174
	v_fma_f32 v174, v176, s88, -v186
	v_add_f32_e32 v178, v250, v178
	v_exp_f32_e32 v229, v174
	v_fma_f32 v174, v177, s88, -v186
	v_add_f32_e32 v178, v251, v178
	v_exp_f32_e32 v230, v174
	v_fma_f32 v170, v170, s88, -v186
	v_add_f32_e32 v174, v252, v178
	v_exp_f32_e32 v232, v170
	v_fma_f32 v170, v171, s88, -v186
	v_add_f32_e32 v174, v231, v174
	v_exp_f32_e32 v228, v170
	v_fma_f32 v170, v172, s88, -v186
	v_add_f32_e32 v174, v229, v174
	v_exp_f32_e32 v196, v170
	v_fma_f32 v170, v173, s88, -v186
	v_add_f32_e32 v174, v230, v174
	v_exp_f32_e32 v173, v170
	v_add_f32_e32 v170, v232, v174
	v_add_f32_e32 v170, v228, v170
	v_add_f32_e32 v170, v196, v170
	v_add_f32_e32 v170, v173, v170
	v_add_f32_e32 v224, v224, v170
	v_max3_f32 v170, v189, v150, v151
	v_max3_f32 v170, v170, v152, v153
	v_max3_f32 v170, v170, v142, v143
	v_max3_f32 v170, v170, v144, v145
	v_mov_b32_e32 v171, v170
	s_nop 1
	v_permlane16_swap_b32_e32 v170, v171
	v_max_f32_e32 v170, v170, v171
	v_mov_b32_e32 v171, v170
	s_nop 1
	v_permlane32_swap_b32_e32 v170, v171
	v_max_f32_e32 v170, v170, v171
	v_add_f32_e32 v171, 0x4259535f, v223
	v_cmp_gt_f32_e32 vcc, v170, v171
	s_cbranch_vccz .LBB0_826
	v_max_f32_e32 v170, v170, v170
	v_max_f32_e32 v171, v223, v223
	v_max_f32_e32 v197, v171, v170
	v_cmp_neq_f32_e32 vcc, s81, v197
	s_nop 1
	v_cndmask_b32_e32 v170, 0, v197, vcc
	v_sub_f32_e32 v170, v223, v170
	v_mul_f32_e32 v170, 0x3e16c740, v170
	v_exp_f32_e32 v170, v170
	v_mov_b32_e32 v223, v197
	v_mul_f32_e32 v225, v225, v170
	v_pk_mul_f32 v[84:85], v[84:85], v[170:171] op_sel_hi:[1,0]
	v_pk_mul_f32 v[82:83], v[82:83], v[170:171] op_sel_hi:[1,0]
	v_pk_mul_f32 v[80:81], v[80:81], v[170:171] op_sel_hi:[1,0]
	v_pk_mul_f32 v[78:79], v[78:79], v[170:171] op_sel_hi:[1,0]
	v_pk_mul_f32 v[72:73], v[72:73], v[170:171] op_sel_hi:[1,0]
	v_pk_mul_f32 v[70:71], v[70:71], v[170:171] op_sel_hi:[1,0]
	v_pk_mul_f32 v[64:65], v[64:65], v[170:171] op_sel_hi:[1,0]
	v_pk_mul_f32 v[62:63], v[62:63], v[170:171] op_sel_hi:[1,0]
	s_branch .LBB0_827
.LBB0_826:
	v_mov_b32_e32 v197, v223

; #define LAS __attribute__((address_space(3)))
; template <int NT, int DQK, int DV, int MODE, int PD, class Src> ...
;     ...
; #pragma unroll
;   for (int u = 0; u < PD; ++u) if (kc0 + u < kc1) ABL_LOAD(u, kc0 + u);
;   for (int kcb = kc0; kcb < kc1; kcb += PD) {
; #pragma unroll
;     for (int u = 0; u < PD; ++u) {
;       const int kc = kcb + u;
;       if (kc < kc1) {
;         LAS unsigned char* buf = lds + ((kc - kc0) & 1) * BUF;
; #pragma unroll
;         for (int rr = 0; rr < NKR; ++rr) { const int idx = tid + 512 * rr; if (idx < NKI) { const int row = idx / KCH, ch = idx % KCH; *(LAS u32x4*)(buf + row * KSTR + ch * 16) = kreg[u][rr]; } }
; #pragma unroll
;         for (int rr = 0; rr < NVR; ++rr) { const int idx = tid + 512 * rr; if (idx < NVI) { const int row = idx / VCH, ch = idx % VCH; *(LAS u32x4*)(buf + KB + row * VSTR + ch * 16) = vreg[u][rr]; } }
;         if (kc + PD < kc1) ABL_LOAD(u, kc + PD);
.LBB0_845:
	s_lshl_b32 s8, s72, 6
	s_mul_hi_u32 s101, s8, s82
	s_mul_i32 s100, s8, s82
	v_lshl_add_u64 v[50:51], v[208:209], 0, s[100:101]
	v_lshl_add_u64 v[52:53], v[212:213], 0, s[40:41]
	s_mov_b64 s[72:73], 0x160a0000
	v_lshl_add_u64 v[52:53], v[52:53], 0, s[72:73]
	v_cndmask_b32_e64 v50, v52, v50, s[16:17]
	v_cndmask_b32_e64 v51, v53, v51, s[16:17]
	global_load_dwordx4 v[50:53], v[50:51], off
	v_lshl_add_u64 v[54:55], v[216:217], 0, s[40:41]
	v_add_co_u32_e32 v54, vcc, 0x160a0000, v54
	s_nop 1
	v_addc_co_u32_e32 v55, vcc, 0, v55, vcc
	global_load_dwordx4 v[54:57], v[54:55], off offset:128
	s_and_saveexec_b64 s[20:21], s[12:13]
	s_cbranch_execz .Lpfk_2
	v_lshl_add_u64 v[58:59], v[210:211], 0, s[100:101]
	v_lshl_add_u64 v[60:61], v[214:215], 0, s[40:41]
	s_mov_b64 s[8:9], 0x160a0000
	v_lshl_add_u64 v[60:61], v[60:61], 0, s[8:9]
	v_cndmask_b32_e64 v58, v60, v58, s[18:19]
	v_cndmask_b32_e64 v59, v61, v59, s[18:19]
	global_load_dwordx4 v[58:61], v[58:59], off

; __device__ __forceinline__ float ex2(float x) { return __builtin_amdgcn_exp2f(x); }
;   __device__ __forceinline__ bf16_t* W() const { return (bf16_t*)(ws + WS_W); }
; template <int NT, int NKK, int NDT, int MODE, bool MASK> ...
;     ...
;   for (int j = 0; j < NT; ++j) {
;     float mx = -INFINITY;
; #pragma unroll
;     for (int t = 0; t < 4; ++t)
; #pragma unroll
;       for (int i = 0; i < 4; ++i) {
;         if (MASK) { const int kp = kpos0 + 16 * t + 4 * lg + i; if (!mask_ok<MODE>(tq[j], kp, W)) s[j][t][i] = -INFINITY; }
;         mx = fmaxf(mx, s[j][t][i]);
;       }
;     mx = max_x16_x32(mx);
;     if (__any(mx > m[j] + 8.0f / c)) {
;       const float mnew = fmaxf(m[j], mx);
;       const float ms2 = (mnew == -INFINITY) ? 0.f : mnew;
;       const float alpha = ex2((m[j] - ms2) * c);
;       m[j] = mnew; l[j] *= alpha;
; #pragma unroll
;       for (int dt = 0; dt < NDT; ++dt) o[j][dt] *= alpha;
;     }
.LBB0_854:
	v_mul_f32_e32 v186, 0x3e16c740, v187
	v_cmp_neq_f32_e32 vcc, s81, v187
	s_nop 1
	v_cndmask_b32_e32 v186, 0, v186, vcc
	v_fma_f32 v182, v182, s88, -v186
	v_exp_f32_e32 v205, v182
	v_fma_f32 v182, v183, s88, -v186
	v_exp_f32_e32 v207, v182
	v_fma_f32 v182, v184, s88, -v186
	v_exp_f32_e32 v246, v182
	v_fma_f32 v182, v185, s88, -v186
	v_exp_f32_e32 v247, v182
	v_fma_f32 v178, v178, s88, -v186
	v_exp_f32_e32 v248, v178
	v_fma_f32 v178, v179, s88, -v186
	v_add_f32_e32 v182, v207, v205
	v_exp_f32_e32 v249, v178
	v_fma_f32 v178, v180, s88, -v186
	v_add_f32_e32 v182, v246, v182
	v_exp_f32_e32 v250, v178
	v_fma_f32 v178, v181, s88, -v186
	v_add_f32_e32 v182, v247, v182
	v_exp_f32_e32 v251, v178
	v_fma_f32 v174, v174, s88, -v186
	v_add_f32_e32 v178, v248, v182
	v_exp_f32_e32 v252, v174
	v_fma_f32 v174, v175, s88, -v186
	v_add_f32_e32 v178, v249, v178
	v_exp_f32_e32 v231, v174
	v_fma_f32 v174, v176, s88, -v186
	v_add_f32_e32 v178, v250, v178
	v_exp_f32_e32 v229, v174
	v_fma_f32 v174, v177, s88, -v186
	v_add_f32_e32 v178, v251, v178
	v_exp_f32_e32 v230, v174
	v_fma_f32 v170, v170, s88, -v186
	v_add_f32_e32 v174, v252, v178
	v_exp_f32_e32 v232, v170
	v_fma_f32 v170, v171, s88, -v186
	v_add_f32_e32 v174, v231, v174
	v_exp_f32_e32 v228, v170
	v_fma_f32 v170, v172, s88, -v186
	v_add_f32_e32 v174, v229, v174
	v_exp_f32_e32 v196, v170
	v_fma_f32 v170, v173, s88, -v186
	v_add_f32_e32 v174, v230, v174
	v_exp_f32_e32 v173, v170
	v_add_f32_e32 v170, v232, v174
	v_add_f32_e32 v170, v228, v170
	v_add_f32_e32 v170, v196, v170
	v_add_f32_e32 v170, v173, v170
	v_add_f32_e32 v224, v224, v170
	v_max3_f32 v170, v189, v150, v151
	v_max3_f32 v170, v170, v152, v153
	v_max3_f32 v170, v170, v142, v143
	v_max3_f32 v170, v170, v144, v145
	v_mov_b32_e32 v171, v170
	s_nop 1
	v_permlane16_swap_b32_e32 v170, v171
	v_max_f32_e32 v170, v170, v171
	v_mov_b32_e32 v171, v170
	s_nop 1
	v_permlane32_swap_b32_e32 v170, v171
	v_max_f32_e32 v170, v170, v171
	v_add_f32_e32 v171, 0x4259535f, v223
	v_cmp_gt_f32_e32 vcc, v170, v171
	s_cbranch_vccz .LBB0_866
	v_max_f32_e32 v170, v170, v170
	v_max_f32_e32 v171, v223, v223
	v_max_f32_e32 v197, v171, v170
	v_cmp_neq_f32_e32 vcc, s81, v197
	s_nop 1
	v_cndmask_b32_e32 v170, 0, v197, vcc
	v_sub_f32_e32 v170, v223, v170
	v_mul_f32_e32 v170, 0x3e16c740, v170
	v_exp_f32_e32 v170, v170
	v_mov_b32_e32 v223, v197
	v_mul_f32_e32 v225, v225, v170
	v_pk_mul_f32 v[84:85], v[84:85], v[170:171] op_sel_hi:[1,0]
	v_pk_mul_f32 v[82:83], v[82:83], v[170:171] op_sel_hi:[1,0]
	v_pk_mul_f32 v[80:81], v[80:81], v[170:171] op_sel_hi:[1,0]
	v_pk_mul_f32 v[78:79], v[78:79], v[170:171] op_sel_hi:[1,0]
	v_pk_mul_f32 v[72:73], v[72:73], v[170:171] op_sel_hi:[1,0]
	v_pk_mul_f32 v[70:71], v[70:71], v[170:171] op_sel_hi:[1,0]
	v_pk_mul_f32 v[64:65], v[64:65], v[170:171] op_sel_hi:[1,0]
	v_pk_mul_f32 v[62:63], v[62:63], v[170:171] op_sel_hi:[1,0]
	s_branch .LBB0_867
.LBB0_866:
	v_mov_b32_e32 v197, v223

; #define LAS __attribute__((address_space(3)))
; template <int NT, int DQK, int DV, int MODE, int PD, class Src> ...
;     ...
; #pragma unroll
;   for (int u = 0; u < PD; ++u) if (kc0 + u < kc1) ABL_LOAD(u, kc0 + u);
;   for (int kcb = kc0; kcb < kc1; kcb += PD) {
; #pragma unroll
;     for (int u = 0; u < PD; ++u) {
;       const int kc = kcb + u;
;       if (kc < kc1) {
;         LAS unsigned char* buf = lds + ((kc - kc0) & 1) * BUF;
; #pragma unroll
;         for (int rr = 0; rr < NKR; ++rr) { const int idx = tid + 512 * rr; if (idx < NKI) { const int row = idx / KCH, ch = idx % KCH; *(LAS u32x4*)(buf + row * KSTR + ch * 16) = kreg[u][rr]; } }
; #pragma unroll
;         for (int rr = 0; rr < NVR; ++rr) { const int idx = tid + 512 * rr; if (idx < NVI) { const int row = idx / VCH, ch = idx % VCH; *(LAS u32x4*)(buf + KB + row * VSTR + ch * 16) = vreg[u][rr]; } }
;         if (kc + PD < kc1) ABL_LOAD(u, kc + PD);
.LBB0_935:
	s_or_b64 exec, exec, s[20:21]
	s_add_i32 s44, s58, 3
	s_cmp_ge_u32 s44, s35
	s_cselect_b64 s[64:65], -1, 0
	s_cmp_lt_u32 s44, s35
	s_cbranch_scc0 .LBB0_941
	s_lshl_b32 s8, s44, 6
	s_mul_hi_u32 s101, s8, s82
	s_mul_i32 s100, s8, s82
	v_lshl_add_u64 v[26:27], v[208:209], 0, s[100:101]
	v_lshl_add_u64 v[28:29], v[212:213], 0, s[66:67]
	v_lshl_add_u64 v[28:29], v[28:29], 0, s[78:79]
	v_cndmask_b32_e64 v26, v28, v26, s[16:17]
	v_cndmask_b32_e64 v27, v29, v27, s[16:17]
	global_load_dwordx4 v[26:29], v[26:27], off
	v_lshl_add_u64 v[34:35], v[216:217], 0, s[66:67]
	v_add_co_u32_e32 v34, vcc, 0x16060000, v34
	s_nop 1
	v_addc_co_u32_e32 v35, vcc, 0, v35, vcc
	global_load_dwordx4 v[34:37], v[34:35], off offset:128
	s_and_saveexec_b64 s[20:21], s[12:13]
	s_cbranch_execz .Lpfk_3
	v_lshl_add_u64 v[30:31], v[210:211], 0, s[100:101]
	v_lshl_add_u64 v[32:33], v[214:215], 0, s[66:67]
	v_lshl_add_u64 v[32:33], v[32:33], 0, s[78:79]
	v_cndmask_b32_e64 v30, v32, v30, s[18:19]
	v_cndmask_b32_e64 v31, v33, v31, s[18:19]
	global_load_dwordx4 v[30:33], v[30:31], off

; __device__ __forceinline__ float ex2(float x) { return __builtin_amdgcn_exp2f(x); }
;   __device__ __forceinline__ bf16_t* W() const { return (bf16_t*)(ws + WS_W); }
; template <int NT, int NKK, int NDT, int MODE, bool MASK> ...
;     ...
;   for (int j = 0; j < NT; ++j) {
;     float mx = -INFINITY;
; #pragma unroll
;     for (int t = 0; t < 4; ++t)
; #pragma unroll
;       for (int i = 0; i < 4; ++i) {
;         if (MASK) { const int kp = kpos0 + 16 * t + 4 * lg + i; if (!mask_ok<MODE>(tq[j], kp, W)) s[j][t][i] = -INFINITY; }
;         mx = fmaxf(mx, s[j][t][i]);
;       }
;     mx = max_x16_x32(mx);
;     if (__any(mx > m[j] + 8.0f / c)) {
;       const float mnew = fmaxf(m[j], mx);
;       const float ms2 = (mnew == -INFINITY) ? 0.f : mnew;
;       const float alpha = ex2((m[j] - ms2) * c);
;       m[j] = mnew; l[j] *= alpha;
; #pragma unroll
;       for (int dt = 0; dt < NDT; ++dt) o[j][dt] *= alpha;
;     }
.LBB0_945:
	v_mul_f32_e32 v186, 0x3e16c740, v187
	v_cmp_neq_f32_e32 vcc, s81, v187
	s_nop 1
	v_cndmask_b32_e32 v186, 0, v186, vcc
	v_fma_f32 v182, v182, s88, -v186
	v_exp_f32_e32 v205, v182
	v_fma_f32 v182, v183, s88, -v186
	v_exp_f32_e32 v207, v182
	v_fma_f32 v182, v184, s88, -v186
	v_exp_f32_e32 v246, v182
	v_fma_f32 v182, v185, s88, -v186
	v_exp_f32_e32 v247, v182
	v_fma_f32 v178, v178, s88, -v186
	v_exp_f32_e32 v248, v178
	v_fma_f32 v178, v179, s88, -v186
	v_add_f32_e32 v182, v207, v205
	v_exp_f32_e32 v249, v178
	v_fma_f32 v178, v180, s88, -v186
	v_add_f32_e32 v182, v246, v182
	v_exp_f32_e32 v250, v178
	v_fma_f32 v178, v181, s88, -v186
	v_add_f32_e32 v182, v247, v182
	v_exp_f32_e32 v251, v178
	v_fma_f32 v174, v174, s88, -v186
	v_add_f32_e32 v178, v248, v182
	v_exp_f32_e32 v252, v174
	v_fma_f32 v174, v175, s88, -v186
	v_add_f32_e32 v178, v249, v178
	v_exp_f32_e32 v231, v174
	v_fma_f32 v174, v176, s88, -v186
	v_add_f32_e32 v178, v250, v178
	v_exp_f32_e32 v229, v174
	v_fma_f32 v174, v177, s88, -v186
	v_add_f32_e32 v178, v251, v178
	v_exp_f32_e32 v230, v174
	v_fma_f32 v170, v170, s88, -v186
	v_add_f32_e32 v174, v252, v178
	v_exp_f32_e32 v232, v170
	v_fma_f32 v170, v171, s88, -v186
	v_add_f32_e32 v174, v231, v174
	v_exp_f32_e32 v228, v170
	v_fma_f32 v170, v172, s88, -v186
	v_add_f32_e32 v174, v229, v174
	v_exp_f32_e32 v196, v170
	v_fma_f32 v170, v173, s88, -v186
	v_add_f32_e32 v174, v230, v174
	v_exp_f32_e32 v173, v170
	v_add_f32_e32 v170, v232, v174
	v_add_f32_e32 v170, v228, v170
	v_add_f32_e32 v170, v196, v170
	v_add_f32_e32 v170, v173, v170
	v_add_f32_e32 v224, v224, v170
	v_max3_f32 v170, v189, v150, v151
	v_max3_f32 v170, v170, v152, v153
	v_max3_f32 v170, v170, v142, v143
	v_max3_f32 v170, v170, v144, v145
	v_mov_b32_e32 v171, v170
	s_nop 1
	v_permlane16_swap_b32_e32 v170, v171
	v_max_f32_e32 v170, v170, v171
	v_mov_b32_e32 v171, v170
	s_nop 1
	v_permlane32_swap_b32_e32 v170, v171
	v_max_f32_e32 v170, v170, v171
	v_add_f32_e32 v171, 0x4259535f, v223
	v_cmp_gt_f32_e32 vcc, v170, v171
	s_cbranch_vccz .LBB0_959
	v_max_f32_e32 v170, v170, v170
	v_max_f32_e32 v171, v223, v223
	v_max_f32_e32 v197, v171, v170
	v_cmp_neq_f32_e32 vcc, s81, v197
	s_nop 1
	v_cndmask_b32_e32 v170, 0, v197, vcc
	v_sub_f32_e32 v170, v223, v170
	v_mul_f32_e32 v170, 0x3e16c740, v170
	v_exp_f32_e32 v170, v170
	v_mov_b32_e32 v223, v197
	v_mul_f32_e32 v225, v225, v170
	v_pk_mul_f32 v[84:85], v[84:85], v[170:171] op_sel_hi:[1,0]
	v_pk_mul_f32 v[82:83], v[82:83], v[170:171] op_sel_hi:[1,0]
	v_pk_mul_f32 v[80:81], v[80:81], v[170:171] op_sel_hi:[1,0]
	v_pk_mul_f32 v[78:79], v[78:79], v[170:171] op_sel_hi:[1,0]
	v_pk_mul_f32 v[72:73], v[72:73], v[170:171] op_sel_hi:[1,0]
	v_pk_mul_f32 v[70:71], v[70:71], v[170:171] op_sel_hi:[1,0]
	v_pk_mul_f32 v[64:65], v[64:65], v[170:171] op_sel_hi:[1,0]
	v_pk_mul_f32 v[62:63], v[62:63], v[170:171] op_sel_hi:[1,0]
	s_branch .LBB0_960
.LBB0_959:
	v_mov_b32_e32 v197, v223

; #define LAS __attribute__((address_space(3)))
; template <int NT, int DQK, int DV, int MODE, int PD, class Src> ...
;     ...
; #pragma unroll
;   for (int u = 0; u < PD; ++u) if (kc0 + u < kc1) ABL_LOAD(u, kc0 + u);
;   for (int kcb = kc0; kcb < kc1; kcb += PD) {
; #pragma unroll
;     for (int u = 0; u < PD; ++u) {
;       const int kc = kcb + u;
;       if (kc < kc1) {
;         LAS unsigned char* buf = lds + ((kc - kc0) & 1) * BUF;
; #pragma unroll
;         for (int rr = 0; rr < NKR; ++rr) { const int idx = tid + 512 * rr; if (idx < NKI) { const int row = idx / KCH, ch = idx % KCH; *(LAS u32x4*)(buf + row * KSTR + ch * 16) = kreg[u][rr]; } }
; #pragma unroll
;         for (int rr = 0; rr < NVR; ++rr) { const int idx = tid + 512 * rr; if (idx < NVI) { const int row = idx / VCH, ch = idx % VCH; *(LAS u32x4*)(buf + KB + row * VSTR + ch * 16) = vreg[u][rr]; } }
;         if (kc + PD < kc1) ABL_LOAD(u, kc + PD);
.LBB0_978:
	s_lshl_b32 s8, s58, 6
	s_addk_i32 s8, 0x100
	s_mul_hi_u32 s101, s8, s82
	s_mul_i32 s100, s8, s82
	v_lshl_add_u64 v[38:39], v[208:209], 0, s[100:101]
	v_lshl_add_u64 v[40:41], v[212:213], 0, s[66:67]
	s_mov_b64 s[68:69], 0x16080000
	v_lshl_add_u64 v[40:41], v[40:41], 0, s[68:69]
	v_cndmask_b32_e64 v38, v40, v38, s[16:17]
	v_cndmask_b32_e64 v39, v41, v39, s[16:17]
	global_load_dwordx4 v[38:41], v[38:39], off
	v_lshl_add_u64 v[42:43], v[216:217], 0, s[66:67]
	v_add_co_u32_e32 v42, vcc, 0x16080000, v42
	s_nop 1
	v_addc_co_u32_e32 v43, vcc, 0, v43, vcc
	global_load_dwordx4 v[42:45], v[42:43], off offset:128
	s_and_saveexec_b64 s[20:21], s[12:13]
	s_cbranch_execz .Lpfk_4
	v_lshl_add_u64 v[46:47], v[210:211], 0, s[100:101]
	v_lshl_add_u64 v[48:49], v[214:215], 0, s[66:67]
	s_mov_b64 s[8:9], 0x16080000
	v_lshl_add_u64 v[48:49], v[48:49], 0, s[8:9]
	v_cndmask_b32_e64 v46, v48, v46, s[18:19]
	v_cndmask_b32_e64 v47, v49, v47, s[18:19]
	global_load_dwordx4 v[46:49], v[46:47], off

; __device__ __forceinline__ float ex2(float x) { return __builtin_amdgcn_exp2f(x); }
;   __device__ __forceinline__ bf16_t* W() const { return (bf16_t*)(ws + WS_W); }
; template <int NT, int NKK, int NDT, int MODE, bool MASK> ...
;     ...
;   for (int j = 0; j < NT; ++j) {
;     float mx = -INFINITY;
; #pragma unroll
;     for (int t = 0; t < 4; ++t)
; #pragma unroll
;       for (int i = 0; i < 4; ++i) {
;         if (MASK) { const int kp = kpos0 + 16 * t + 4 * lg + i; if (!mask_ok<MODE>(tq[j], kp, W)) s[j][t][i] = -INFINITY; }
;         mx = fmaxf(mx, s[j][t][i]);
;       }
;     mx = max_x16_x32(mx);
;     if (__any(mx > m[j] + 8.0f / c)) {
;       const float mnew = fmaxf(m[j], mx);
;       const float ms2 = (mnew == -INFINITY) ? 0.f : mnew;
;       const float alpha = ex2((m[j] - ms2) * c);
;       m[j] = mnew; l[j] *= alpha;
; #pragma unroll
;       for (int dt = 0; dt < NDT; ++dt) o[j][dt] *= alpha;
;     }
.LBB0_987:
	v_mul_f32_e32 v186, 0x3e16c740, v187
	v_cmp_neq_f32_e32 vcc, s81, v187
	s_nop 1
	v_cndmask_b32_e32 v186, 0, v186, vcc
	v_fma_f32 v182, v182, s88, -v186
	v_exp_f32_e32 v205, v182
	v_fma_f32 v182, v183, s88, -v186
	v_exp_f32_e32 v207, v182
	v_fma_f32 v182, v184, s88, -v186
	v_exp_f32_e32 v246, v182
	v_fma_f32 v182, v185, s88, -v186
	v_exp_f32_e32 v247, v182
	v_fma_f32 v178, v178, s88, -v186
	v_exp_f32_e32 v248, v178
	v_fma_f32 v178, v179, s88, -v186
	v_add_f32_e32 v182, v207, v205
	v_exp_f32_e32 v249, v178
	v_fma_f32 v178, v180, s88, -v186
	v_add_f32_e32 v182, v246, v182
	v_exp_f32_e32 v250, v178
	v_fma_f32 v178, v181, s88, -v186
	v_add_f32_e32 v182, v247, v182
	v_exp_f32_e32 v251, v178
	v_fma_f32 v174, v174, s88, -v186
	v_add_f32_e32 v178, v248, v182
	v_exp_f32_e32 v252, v174
	v_fma_f32 v174, v175, s88, -v186
	v_add_f32_e32 v178, v249, v178
	v_exp_f32_e32 v231, v174
	v_fma_f32 v174, v176, s88, -v186
	v_add_f32_e32 v178, v250, v178
	v_exp_f32_e32 v229, v174
	v_fma_f32 v174, v177, s88, -v186
	v_add_f32_e32 v178, v251, v178
	v_exp_f32_e32 v230, v174
	v_fma_f32 v170, v170, s88, -v186
	v_add_f32_e32 v174, v252, v178
	v_exp_f32_e32 v232, v170
	v_fma_f32 v170, v171, s88, -v186
	v_add_f32_e32 v174, v231, v174
	v_exp_f32_e32 v228, v170
	v_fma_f32 v170, v172, s88, -v186
	v_add_f32_e32 v174, v229, v174
	v_exp_f32_e32 v196, v170
	v_fma_f32 v170, v173, s88, -v186
	v_add_f32_e32 v174, v230, v174
	v_exp_f32_e32 v173, v170
	v_add_f32_e32 v170, v232, v174
	v_add_f32_e32 v170, v228, v170
	v_add_f32_e32 v170, v196, v170
	v_add_f32_e32 v170, v173, v170
	v_add_f32_e32 v224, v224, v170
	v_max3_f32 v170, v189, v150, v151
	v_max3_f32 v170, v170, v152, v153
	v_max3_f32 v170, v170, v142, v143
	v_max3_f32 v170, v170, v144, v145
	v_mov_b32_e32 v171, v170
	s_nop 1
	v_permlane16_swap_b32_e32 v170, v171
	v_max_f32_e32 v170, v170, v171
	v_mov_b32_e32 v171, v170
	s_nop 1
	v_permlane32_swap_b32_e32 v170, v171
	v_max_f32_e32 v170, v170, v171
	v_add_f32_e32 v171, 0x4259535f, v223
	v_cmp_gt_f32_e32 vcc, v170, v171
	s_cbranch_vccz .LBB0_999
	v_max_f32_e32 v170, v170, v170
	v_max_f32_e32 v171, v223, v223
	v_max_f32_e32 v197, v171, v170
	v_cmp_neq_f32_e32 vcc, s81, v197
	s_nop 1
	v_cndmask_b32_e32 v170, 0, v197, vcc
	v_sub_f32_e32 v170, v223, v170
	v_mul_f32_e32 v170, 0x3e16c740, v170
	v_exp_f32_e32 v170, v170
	v_mov_b32_e32 v223, v197
	v_mul_f32_e32 v225, v225, v170
	v_pk_mul_f32 v[84:85], v[84:85], v[170:171] op_sel_hi:[1,0]
	v_pk_mul_f32 v[82:83], v[82:83], v[170:171] op_sel_hi:[1,0]
	v_pk_mul_f32 v[80:81], v[80:81], v[170:171] op_sel_hi:[1,0]
	v_pk_mul_f32 v[78:79], v[78:79], v[170:171] op_sel_hi:[1,0]
	v_pk_mul_f32 v[72:73], v[72:73], v[170:171] op_sel_hi:[1,0]
	v_pk_mul_f32 v[70:71], v[70:71], v[170:171] op_sel_hi:[1,0]
	v_pk_mul_f32 v[64:65], v[64:65], v[170:171] op_sel_hi:[1,0]
	v_pk_mul_f32 v[62:63], v[62:63], v[170:171] op_sel_hi:[1,0]
	s_branch .LBB0_1000
.LBB0_999:
	v_mov_b32_e32 v197, v223

; template <int NT, int DQK, int DV, int MODE, int PD, class Src> ...
;     ...
;         if (kc + PD < kc1) ABL_LOAD(u, kc + PD);
.LBB0_1018:
	s_lshl_b32 s8, s58, 6
	s_mul_hi_u32 s101, s8, s82
	s_mul_i32 s100, s8, s82
	v_lshl_add_u64 v[50:51], v[208:209], 0, s[100:101]
	v_lshl_add_u64 v[52:53], v[212:213], 0, s[66:67]
	s_mov_b64 s[58:59], 0x160a0000
	v_lshl_add_u64 v[52:53], v[52:53], 0, s[58:59]
	v_cndmask_b32_e64 v50, v52, v50, s[16:17]
	v_cndmask_b32_e64 v51, v53, v51, s[16:17]
	global_load_dwordx4 v[50:53], v[50:51], off
	v_lshl_add_u64 v[54:55], v[216:217], 0, s[66:67]
	v_add_co_u32_e32 v54, vcc, 0x160a0000, v54
	s_nop 1
	v_addc_co_u32_e32 v55, vcc, 0, v55, vcc
	global_load_dwordx4 v[54:57], v[54:55], off offset:128
	s_and_saveexec_b64 s[20:21], s[12:13]
	s_cbranch_execz .Lpfk_5
	v_lshl_add_u64 v[58:59], v[210:211], 0, s[100:101]
	v_lshl_add_u64 v[60:61], v[214:215], 0, s[66:67]
	s_mov_b64 s[8:9], 0x160a0000
	v_lshl_add_u64 v[60:61], v[60:61], 0, s[8:9]
	v_cndmask_b32_e64 v58, v60, v58, s[18:19]
	v_cndmask_b32_e64 v59, v61, v59, s[18:19]
	global_load_dwordx4 v[58:61], v[58:59], off

; __device__ __forceinline__ float ex2(float x) { return __builtin_amdgcn_exp2f(x); }
;   __device__ __forceinline__ bf16_t* W() const { return (bf16_t*)(ws + WS_W); }
; template <int NT, int NKK, int NDT, int MODE, bool MASK> ...
;     ...
;   for (int j = 0; j < NT; ++j) {
;     float mx = -INFINITY;
; #pragma unroll
;     for (int t = 0; t < 4; ++t)
; #pragma unroll
;       for (int i = 0; i < 4; ++i) {
;         if (MASK) { const int kp = kpos0 + 16 * t + 4 * lg + i; if (!mask_ok<MODE>(tq[j], kp, W)) s[j][t][i] = -INFINITY; }
;         mx = fmaxf(mx, s[j][t][i]);
;       }
;     mx = max_x16_x32(mx);
;     if (__any(mx > m[j] + 8.0f / c)) {
;       const float mnew = fmaxf(m[j], mx);
;       const float ms2 = (mnew == -INFINITY) ? 0.f : mnew;
;       const float alpha = ex2((m[j] - ms2) * c);
;       m[j] = mnew; l[j] *= alpha;
; #pragma unroll
;       for (int dt = 0; dt < NDT; ++dt) o[j][dt] *= alpha;
;     }
;     const float mc = ((m[j] == -INFINITY) ? 0.f : m[j]) * c;
;     float p[4][4], ps = 0.f;
; #pragma unroll
;     for (int t = 0; t < 4; ++t)
; #pragma unroll
;       for (int i = 0; i < 4; ++i) { p[t][i] = ex2(s[j][t][i] * c - mc); ps += p[t][i]; }
;     l[j] += ps;
;     pf[j][0] = pack8(p[0], p[1]); pf[j][1] = pack8(p[2], p[3]);
.LBB0_1027:
	v_mul_f32_e32 v186, 0x3e16c740, v187
	v_cmp_neq_f32_e32 vcc, s81, v187
	s_nop 1
	v_cndmask_b32_e32 v186, 0, v186, vcc
	v_fma_f32 v182, v182, s88, -v186
	v_exp_f32_e32 v205, v182
	v_fma_f32 v182, v183, s88, -v186
	v_exp_f32_e32 v207, v182
	v_fma_f32 v182, v184, s88, -v186
	v_exp_f32_e32 v246, v182
	v_fma_f32 v182, v185, s88, -v186
	v_exp_f32_e32 v247, v182
	v_fma_f32 v178, v178, s88, -v186
	v_exp_f32_e32 v248, v178
	v_fma_f32 v178, v179, s88, -v186
	v_add_f32_e32 v182, v207, v205
	v_exp_f32_e32 v249, v178
	v_fma_f32 v178, v180, s88, -v186
	v_add_f32_e32 v182, v246, v182
	v_exp_f32_e32 v250, v178
	v_fma_f32 v178, v181, s88, -v186
	v_add_f32_e32 v182, v247, v182
	v_exp_f32_e32 v251, v178
	v_fma_f32 v174, v174, s88, -v186
	v_add_f32_e32 v178, v248, v182
	v_exp_f32_e32 v252, v174
	v_fma_f32 v174, v175, s88, -v186
	v_add_f32_e32 v178, v249, v178
	v_exp_f32_e32 v231, v174
	v_fma_f32 v174, v176, s88, -v186
	v_add_f32_e32 v178, v250, v178
	v_exp_f32_e32 v229, v174
	v_fma_f32 v174, v177, s88, -v186
	v_add_f32_e32 v178, v251, v178
	v_exp_f32_e32 v230, v174
	v_fma_f32 v170, v170, s88, -v186
	v_add_f32_e32 v174, v252, v178
	v_exp_f32_e32 v232, v170
	v_fma_f32 v170, v171, s88, -v186
	v_add_f32_e32 v174, v231, v174
	v_exp_f32_e32 v228, v170
	v_fma_f32 v170, v172, s88, -v186
	v_add_f32_e32 v174, v229, v174
	v_exp_f32_e32 v196, v170
	v_fma_f32 v170, v173, s88, -v186
	v_add_f32_e32 v174, v230, v174
	v_exp_f32_e32 v173, v170
	v_add_f32_e32 v170, v232, v174
	v_add_f32_e32 v170, v228, v170
	v_add_f32_e32 v170, v196, v170
	v_add_f32_e32 v170, v173, v170
	v_add_f32_e32 v224, v224, v170
	v_max3_f32 v170, v189, v150, v151
	v_max3_f32 v170, v170, v152, v153
	v_max3_f32 v170, v170, v142, v143
	v_max3_f32 v170, v170, v144, v145
	v_mov_b32_e32 v171, v170
	s_nop 1
	v_permlane16_swap_b32_e32 v170, v171
	v_max_f32_e32 v170, v170, v171
	v_mov_b32_e32 v171, v170
	s_nop 1
	v_permlane32_swap_b32_e32 v170, v171
	v_max_f32_e32 v170, v170, v171
	v_add_f32_e32 v171, 0x4259535f, v223
	v_cmp_gt_f32_e32 vcc, v170, v171
	s_cbranch_vccz .LBB0_1039
	v_max_f32_e32 v170, v170, v170
	v_max_f32_e32 v171, v223, v223
	v_max_f32_e32 v197, v171, v170
	v_cmp_neq_f32_e32 vcc, s81, v197
	s_nop 1
	v_cndmask_b32_e32 v170, 0, v197, vcc
	v_sub_f32_e32 v170, v223, v170
	v_mul_f32_e32 v170, 0x3e16c740, v170
	v_exp_f32_e32 v170, v170
	v_mov_b32_e32 v223, v197
	v_mul_f32_e32 v225, v225, v170
	v_pk_mul_f32 v[84:85], v[84:85], v[170:171] op_sel_hi:[1,0]
	v_pk_mul_f32 v[82:83], v[82:83], v[170:171] op_sel_hi:[1,0]
	v_pk_mul_f32 v[80:81], v[80:81], v[170:171] op_sel_hi:[1,0]
	v_pk_mul_f32 v[78:79], v[78:79], v[170:171] op_sel_hi:[1,0]
	v_pk_mul_f32 v[72:73], v[72:73], v[170:171] op_sel_hi:[1,0]
	v_pk_mul_f32 v[70:71], v[70:71], v[170:171] op_sel_hi:[1,0]
	v_pk_mul_f32 v[64:65], v[64:65], v[170:171] op_sel_hi:[1,0]
	v_pk_mul_f32 v[62:63], v[62:63], v[170:171] op_sel_hi:[1,0]
	s_branch .LBB0_1040
.LBB0_1039:
	v_mov_b32_e32 v197, v223
